# Gin->P2b barrier: 18-tile workgroups sleep (5-d)*100 before polling (they know the 19th round is still running)
# baseline (speedup 1.0000x reference)
.LBB0_149:
	s_or_b64 exec, exec, s[6:7]
	s_load_dword s3, s[84:85], 0x0
	s_waitcnt lgkmcnt(0)
	s_cmp_lg_u32 s3, 0x100
	s_cbranch_scc1 .Lgs_skip
	s_cmp_lt_u32 s93, 36
	s_cbranch_scc1 .Lgs_skip
	s_sub_i32 s3, s93, 36
	s_and_b32 s3, s3, 7
	s_sub_i32 s3, 5, s3
.Lgs_loop:
	s_cmp_lt_i32 s3, 1
	s_cbranch_scc1 .Lgs_skip
	s_sleep 0x64
	s_sub_i32 s3, s3, 1
	s_branch .Lgs_loop
.Lgs_skip:
	v_readlane_b32 s8, v254, 50
	v_mov_b32_e32 v0, 0x3c5e1000
	v_readlane_b32 s9, v254, 51
	s_mul_i32 s2, s2, s94
	s_add_u32 s6, s8, 0x3c5e1000
	s_addc_u32 s7, s9, 0
	v_readlane_b32 s10, v254, 52
	v_readlane_b32 s11, v254, 53
	global_load_dword v0, v0, s[8:9] sc1
	s_waitcnt vmcnt(0)
	v_cmp_le_u32_e32 vcc, s2, v0
	s_cbranch_vccnz .LBB0_152
	v_mov_b32_e32 v0, 0
